# ffn_act loop rewritten by hand: 3 taps for context tokens, border taps by exec mask instead of weight*mask, folded gelu constants + v_rcp, one token ahead in flight, latent grid visited in 8x8 tiles
# speedup vs baseline: 1.1325x; 1.0102x over previous
.Lrb1_start:
	s_waitcnt vmcnt(0) lgkmcnt(0)
	s_cmp_gt_u32 s72, 127
	s_cbranch_scc1 .Lrb1_done
	v_lshrrev_b32_e32 v0, 6, v177
	v_and_b32_e32 v2, 63, v177
	v_readfirstlane_b32 s0, v0
	s_nop 3
	s_and_b32 s1, s72, 7
	s_lshr_b32 s5, s72, 5
	s_lshl_b32 s5, s5, 3
	s_or_b32 s1, s1, s5
	s_bfe_u32 s5, s72, 0x20003
	s_lshl_b32 s6, s1, 21
	s_add_u32 s38, s76, s6
	s_addc_u32 s39, s77, 0
	s_add_u32 s38, s38, 0xb980000
	s_addc_u32 s39, s39, 0
	s_mov_b32 s40, s38
	s_mov_b32 s41, s39
	s_lshr_b32 s6, s1, 4
	s_and_b32 s7, s1, 1
	s_lshl_b32 s6, s6, 1
	s_or_b32 s6, s6, s7
	s_bfe_u32 s7, s1, 0x30001
	s_lshl_b32 s6, s6, 3
	s_or_b32 s6, s6, s7
	s_lshl_b32 s6, s6, 14
	v_readlane_b32 s42, v252, 8
	v_readlane_b32 s43, v252, 9
	s_nop 3
	s_add_u32 s42, s42, s6
	s_addc_u32 s43, s43, 0
	v_and_b32_e32 v3, 15, v2
	v_lshrrev_b32_e32 v4, 4, v2
	s_lshl_b32 s6, s5, 12
	s_and_b32 s7, s0, 3
	s_lshl_b32 s7, s7, 6
	s_add_u32 s6, s6, s7
	v_lshlrev_b32_e32 v5, 8, v3
	v_lshl_add_u32 v5, v4, 4, v5
	v_add_u32_e32 v5, s6, v5
	s_add_u32 s7, s7, 0x4000
	v_lshlrev_b32_e32 v6, 8, v4
	v_lshl_add_u32 v6, v3, 2, v6
	v_add_u32_e32 v6, s7, v6
	v_add_u32_e32 v7, 0x1000, v6
	v_add_u32_e32 v8, 0x2000, v6
	v_add_u32_e32 v9, 0x3000, v6
	v_mul_u32_u24_e32 v0, 0x110, v3
	v_lshl_add_u32 v10, v4, 2, v0
	v_lshl_add_u32 v11, v4, 4, v0
	v_add_u32_e32 v11, s7, v11
	v_subrev_u32_e32 v11, 0x4000, v11
	s_cmp_gt_u32 s0, 3
	s_cbranch_scc1 .Lrb1_helper
	global_load_dwordx4 v[12:15], v5, s[42:43]
	global_load_dwordx4 v[56:59], v5, s[38:39]
	global_load_dword v40, v6, s[38:39]
	global_load_dword v41, v6, s[38:39] offset:1024
	global_load_dword v42, v6, s[38:39] offset:2048
	global_load_dword v43, v6, s[38:39] offset:3072
	global_load_dword v44, v7, s[38:39]
	global_load_dword v45, v7, s[38:39] offset:1024
	global_load_dword v46, v7, s[38:39] offset:2048
	global_load_dword v47, v7, s[38:39] offset:3072
	global_load_dword v48, v8, s[38:39]
	global_load_dword v49, v8, s[38:39] offset:1024
	global_load_dword v50, v8, s[38:39] offset:2048
	global_load_dword v51, v8, s[38:39] offset:3072
	global_load_dword v52, v9, s[38:39]
	global_load_dword v53, v9, s[38:39] offset:1024
	global_load_dword v54, v9, s[38:39] offset:2048
	global_load_dword v55, v9, s[38:39] offset:3072
	s_add_u32 s38, s38, 0x8000
	s_addc_u32 s39, s39, 0
	s_waitcnt vmcnt(0)
	global_load_dwordx4 v[76:79], v5, s[38:39]
	global_load_dword v60, v6, s[38:39]
	global_load_dword v61, v6, s[38:39] offset:1024
	global_load_dword v62, v6, s[38:39] offset:2048
	global_load_dword v63, v6, s[38:39] offset:3072
	global_load_dword v64, v7, s[38:39]
	global_load_dword v65, v7, s[38:39] offset:1024
	global_load_dword v66, v7, s[38:39] offset:2048
	global_load_dword v67, v7, s[38:39] offset:3072
	global_load_dword v68, v8, s[38:39]
	global_load_dword v69, v8, s[38:39] offset:1024
	global_load_dword v70, v8, s[38:39] offset:2048
	global_load_dword v71, v8, s[38:39] offset:3072
	global_load_dword v72, v9, s[38:39]
	global_load_dword v73, v9, s[38:39] offset:1024
	global_load_dword v74, v9, s[38:39] offset:2048
	global_load_dword v75, v9, s[38:39] offset:3072
	s_add_u32 s38, s38, 0x8000
	s_addc_u32 s39, s39, 0
	global_store_dwordx4 v5, v[12:15], s[40:41]
	s_add_u32 s40, s40, 0x8000
	s_addc_u32 s41, s41, 0
	ds_write_b128 v11, v[12:15]
	v_xor_b32_e32 v11, 0x2000, v11
	s_movk_i32 s10, 20
	s_waitcnt lgkmcnt(0)
	s_barrier

.Lrb1_helper:
	s_add_u32 s38, s38, 0x28000
	s_addc_u32 s39, s39, 0
	s_movk_i32 s10, 58
.Lrb1_hwarm:
	s_barrier
	s_sub_u32 s10, s10, 1
	s_cmp_lg_u32 s10, 0
	s_cbranch_scc1 .Lrb1_hwarm
	s_movk_i32 s10, 6
.Lrb1_hloop:
	s_barrier
	s_sub_u32 s10, s10, 1
	s_cmp_lg_u32 s10, 0
	s_cbranch_scc1 .Lrb1_hloop
	s_waitcnt vmcnt(0)

.LBB0_1431:
	s_or_b64 exec, exec, s[0:1]
	s_waitcnt lgkmcnt(0)
	v_mov_b32_e32 v0, v177
	s_barrier
	s_and_b32 s0, s72, 7
	s_lshl_b32 s0, s0, 5
	s_lshr_b32 s1, s72, 3
	s_add_i32 s0, s0, s1
	s_lshl_b32 s0, s0, 9
	s_mul_hi_i32 s1, s74, 0x2e8ba2e9
	s_lshr_b32 s4, s1, 31
	v_add_u32_e32 v0, s0, v0
	s_mov_b32 s0, 0x2e8ba2e9
	v_mul_hi_i32 v1, v0, s0
	s_ashr_i32 s12, s1, 6
	v_lshrrev_b32_e32 v2, 31, v1
	v_ashrrev_i32_e32 v1, 6, v1
	s_add_i32 s12, s12, s4
	v_add_u32_e32 v170, v1, v2
	v_cmp_gt_i32_e32 vcc, s12, v170
	s_and_saveexec_b64 s[4:5], vcc
	s_cbranch_execz .LBB0_1447
	s_mov_b32 s0, 0x580000
	v_cmp_gt_i32_e32 vcc, s0, v0
	s_and_b64 exec, exec, vcc
	s_cbranch_execz .LBB0_1447
	v_mul_i32_i24_e32 v1, 0x160, v170
	v_sub_u32_e32 v0, v0, v1
	v_lshlrev_b32_e32 v80, 3, v0
	v_readlane_b32 s40, v252, 51
	v_ashrrev_i32_e32 v81, 31, v80
	v_readlane_b32 s42, v252, 53
	v_readlane_b32 s43, v252, 54
	v_readlane_b32 s46, v252, 57
	v_readlane_b32 s47, v252, 58
	v_lshlrev_b64 v[72:73], 2, v[80:81]
	s_mov_b64 s[42:43], s[46:47]
	v_lshl_add_u64 v[64:65], s[42:43], 0, v[72:73]
	v_add_co_u32_e32 v8, vcc, 0x2000, v64
	s_mov_b64 s[0:1], 0x2c00
	s_nop 0
	v_addc_co_u32_e32 v9, vcc, 0, v65, vcc
	v_add_co_u32_e32 v16, vcc, 0x5000, v64
	v_lshl_add_u64 v[12:13], v[64:65], 0, s[0:1]
	s_nop 0
	v_addc_co_u32_e32 v17, vcc, 0, v65, vcc
	v_add_co_u32_e32 v24, vcc, 0x8000, v64
	s_mov_b64 s[0:1], 0x5800
	s_nop 0
	v_addc_co_u32_e32 v25, vcc, 0, v65, vcc
	v_add_co_u32_e32 v32, vcc, 0xb000, v64
	v_lshl_add_u64 v[20:21], v[64:65], 0, s[0:1]
	s_nop 0
	v_addc_co_u32_e32 v33, vcc, 0, v65, vcc
	s_mov_b64 s[0:1], 0x8400
	v_add_co_u32_e32 v40, vcc, 0xd000, v64
	v_lshl_add_u64 v[28:29], v[64:65], 0, s[0:1]
	s_mov_b64 s[0:1], 0xb000
	v_addc_co_u32_e32 v41, vcc, 0, v65, vcc
	v_lshl_add_u64 v[36:37], v[64:65], 0, s[0:1]
	s_mov_b64 s[0:1], 0xdc00
	v_add_co_u32_e32 v48, vcc, 0x10000, v64
	v_lshl_add_u64 v[44:45], v[64:65], 0, s[0:1]
	s_mov_b64 s[0:1], 0x10800
	v_addc_co_u32_e32 v49, vcc, 0, v65, vcc
	v_lshl_add_u64 v[52:53], v[64:65], 0, s[0:1]
	s_mov_b64 s[0:1], 0x13400
	v_add_co_u32_e32 v56, vcc, 0x13000, v64
	v_readlane_b32 s44, v252, 55
	v_readlane_b32 s45, v252, 56
	v_readlane_b32 s48, v252, 59
	v_readlane_b32 s49, v252, 60
	v_lshl_add_u64 v[60:61], v[64:65], 0, s[0:1]
	v_addc_co_u32_e32 v57, vcc, 0, v65, vcc
	s_mov_b64 s[0:1], 0x16000
	s_mov_b64 s[44:45], s[48:49]
	global_load_dwordx4 v[0:3], v[64:65], off
	global_load_dwordx4 v[4:7], v[64:65], off offset:16
	v_lshl_add_u64 v[68:69], v[64:65], 0, s[0:1]
	v_add_co_u32_e32 v64, vcc, 0x16000, v64
	v_lshl_add_u64 v[76:77], s[44:45], 0, v[72:73]
	s_nop 0
	v_addc_co_u32_e32 v65, vcc, 0, v65, vcc
	global_load_dwordx4 v[8:11], v[8:9], off offset:3072
	s_nop 0
	global_load_dwordx4 v[12:15], v[12:13], off offset:16
	s_nop 0
	global_load_dwordx4 v[16:19], v[16:17], off offset:2048
	s_nop 0
	global_load_dwordx4 v[20:23], v[20:21], off offset:16
	s_nop 0
	global_load_dwordx4 v[24:27], v[24:25], off offset:1024
	s_nop 0
	global_load_dwordx4 v[28:31], v[28:29], off offset:16
	s_nop 0
	global_load_dwordx4 v[32:35], v[32:33], off
	s_nop 0
	global_load_dwordx4 v[36:39], v[36:37], off offset:16
	s_nop 0
	global_load_dwordx4 v[40:43], v[40:41], off offset:3072
	s_nop 0
	global_load_dwordx4 v[44:47], v[44:45], off offset:16
	s_nop 0
	global_load_dwordx4 v[48:51], v[48:49], off offset:2048
	s_nop 0
	global_load_dwordx4 v[52:55], v[52:53], off offset:16
	s_nop 0
	global_load_dwordx4 v[56:59], v[56:57], off offset:1024
	s_nop 0
	global_load_dwordx4 v[60:63], v[60:61], off offset:16
	s_nop 0
	global_load_dwordx4 v[64:67], v[64:65], off
	s_nop 0
	global_load_dwordx4 v[68:71], v[68:69], off offset:16
	s_nop 0
	global_load_dwordx4 v[72:75], v[76:77], off
	s_nop 0
	global_load_dwordx4 v[76:79], v[76:77], off offset:16
	v_lshlrev_b64 v[80:81], 1, v[80:81]
	v_lshl_add_u64 v[164:165], s[2:3], 0, v[80:81]
	v_lshl_add_u64 v[166:167], s[16:17], 0, v[80:81]
	s_mov_b64 s[60:61], s[16:17]
	s_mov_b64 s[96:97], s[2:3]
	v_mov_b32_e32 v199, v80
	s_mov_b64 s[6:7], 0
	s_movk_i32 s13, 0x4000
	s_movk_i32 s14, 0x1fff
	s_movk_i32 s15, 0x1600
	v_mov_b32_e32 v169, 0
	s_movk_i32 s16, 0xff
	v_mov_b32_e32 v172, v170
	v_readlane_b32 s41, v252, 52
	v_readlane_b32 s50, v252, 61
	v_readlane_b32 s51, v252, 62
	v_readlane_b32 s52, v252, 63
	v_readlane_b32 s53, v253, 0
	v_readlane_b32 s54, v253, 1
	v_readlane_b32 s55, v253, 2
	s_branch .LBB0_1435
	global_store_dwordx4 v[100:101], v[96:99], off sc1
	global_store_dwordx4 v[84:85], v[80:83], off sc1
.LBB0_1435:
	s_waitcnt vmcnt(0) lgkmcnt(0)
	s_mov_b64 s[38:39], exec
	v_and_b32_e32 v200, 0xff, v172
	v_mad_u32_u24 v197, v172, s15, v199
	v_cmp_ne_u32_e64 s[86:87], 0, v200
	v_cmp_ne_u32_e64 s[88:89], s16, v200
	global_load_dwordx4 v[96:99], v197, s[60:61]
	global_load_dwordx4 v[152:155], v197, s[96:97]
	v_subrev_u32_e32 v201, 0x1600, v197
	v_add_u32_e32 v202, 0x1600, v197
	v_cndmask_b32_e64 v201, v197, v201, s[86:87]
	v_cndmask_b32_e64 v202, v197, v202, s[88:89]
	global_load_dwordx4 v[92:95], v201, s[60:61]
	global_load_dwordx4 v[100:103], v202, s[60:61]
	v_add_u32_e32 v172, s12, v172
	v_and_b32_e32 v200, 0xff, v172
	v_mad_u32_u24 v198, v172, s15, v199
	v_cmp_ne_u32_e64 s[50:51], 0, v200
	v_cmp_ne_u32_e64 s[52:53], s16, v200
	global_load_dwordx4 v[132:135], v198, s[60:61]
	global_load_dwordx4 v[156:159], v198, s[96:97]
	v_subrev_u32_e32 v201, 0x1600, v198
	v_add_u32_e32 v202, 0x1600, v198
	v_cndmask_b32_e64 v201, v198, v201, s[50:51]
	v_cndmask_b32_e64 v202, v198, v202, s[52:53]
	global_load_dwordx4 v[128:131], v201, s[60:61]
	global_load_dwordx4 v[136:139], v202, s[60:61]
	v_add_u32_e32 v172, s12, v172
	s_waitcnt vmcnt(4)
	v_lshlrev_b32_e32 v216, 16, v96
	v_and_b32_e32 v217, 0xffff0000, v96
	v_lshlrev_b32_e32 v218, 16, v97
	v_and_b32_e32 v219, 0xffff0000, v97
	v_lshlrev_b32_e32 v220, 16, v98
	v_and_b32_e32 v221, 0xffff0000, v98
	v_lshlrev_b32_e32 v222, 16, v99
	v_and_b32_e32 v223, 0xffff0000, v99
	v_fma_f32 v208, v32, v216, v72
	v_fma_f32 v209, v33, v217, v73
	v_fma_f32 v210, v34, v218, v74
	v_fma_f32 v211, v35, v219, v75
	v_fma_f32 v212, v36, v220, v76
	v_fma_f32 v213, v37, v221, v77
	v_fma_f32 v214, v38, v222, v78
	v_fma_f32 v215, v39, v223, v79
	s_mov_b64 exec, s[86:87]
	s_cbranch_execz .Lact_t1_k3
	v_lshlrev_b32_e32 v216, 16, v92
	v_and_b32_e32 v217, 0xffff0000, v92
	v_lshlrev_b32_e32 v218, 16, v93
	v_and_b32_e32 v219, 0xffff0000, v93
	v_lshlrev_b32_e32 v220, 16, v94
	v_and_b32_e32 v221, 0xffff0000, v94
	v_lshlrev_b32_e32 v222, 16, v95
	v_and_b32_e32 v223, 0xffff0000, v95
	v_fmac_f32_e32 v208, v24, v216
	v_fmac_f32_e32 v209, v25, v217
	v_fmac_f32_e32 v210, v26, v218
	v_fmac_f32_e32 v211, v27, v219
	v_fmac_f32_e32 v212, v28, v220
	v_fmac_f32_e32 v213, v29, v221
	v_fmac_f32_e32 v214, v30, v222
	v_fmac_f32_e32 v215, v31, v223
.Lact_t1_k3:
	s_mov_b64 exec, s[88:89]
	s_cbranch_execz .Lact_t1_k5
	v_lshlrev_b32_e32 v216, 16, v100
	v_and_b32_e32 v217, 0xffff0000, v100
	v_lshlrev_b32_e32 v218, 16, v101
	v_and_b32_e32 v219, 0xffff0000, v101
	v_lshlrev_b32_e32 v220, 16, v102
	v_and_b32_e32 v221, 0xffff0000, v102
	v_lshlrev_b32_e32 v222, 16, v103
	v_and_b32_e32 v223, 0xffff0000, v103
	v_fmac_f32_e32 v208, v40, v216
	v_fmac_f32_e32 v209, v41, v217
	v_fmac_f32_e32 v210, v42, v218
	v_fmac_f32_e32 v211, v43, v219
	v_fmac_f32_e32 v212, v44, v220
	v_fmac_f32_e32 v213, v45, v221
	v_fmac_f32_e32 v214, v46, v222
	v_fmac_f32_e32 v215, v47, v223
.Lact_t1_k5:
	s_mov_b64 exec, s[38:39]
	v_mul_f32_e32 v216, v208, v208
	v_mul_f32_e32 v217, v209, v209
	v_mul_f32_e32 v218, v210, v210
	v_mul_f32_e32 v219, v211, v211
	v_mul_f32_e32 v220, v212, v212
	v_mul_f32_e32 v221, v213, v213
	v_mul_f32_e32 v222, v214, v214
	v_mul_f32_e32 v223, v215, v215
	v_mov_b32_e32 v200, 0x40135761
	v_fmamk_f32 v216, v216, 0x3dd2d3e8, v200
	v_fmamk_f32 v217, v217, 0x3dd2d3e8, v200
	v_fmamk_f32 v218, v218, 0x3dd2d3e8, v200
	v_fmamk_f32 v219, v219, 0x3dd2d3e8, v200
	v_fmamk_f32 v220, v220, 0x3dd2d3e8, v200
	v_fmamk_f32 v221, v221, 0x3dd2d3e8, v200
	v_fmamk_f32 v222, v222, 0x3dd2d3e8, v200
	v_fmamk_f32 v223, v223, 0x3dd2d3e8, v200
	v_mul_f32_e32 v216, v216, v208
	v_mul_f32_e32 v217, v217, v209
	v_mul_f32_e32 v218, v218, v210
	v_mul_f32_e32 v219, v219, v211
	v_mul_f32_e32 v220, v220, v212
	v_mul_f32_e32 v221, v221, v213
	v_mul_f32_e32 v222, v222, v214
	v_mul_f32_e32 v223, v223, v215
	v_exp_f32_e32 v216, v216
	v_exp_f32_e32 v217, v217
	v_exp_f32_e32 v218, v218
	v_exp_f32_e32 v219, v219
	v_exp_f32_e32 v220, v220
	v_exp_f32_e32 v221, v221
	v_exp_f32_e32 v222, v222
	v_exp_f32_e32 v223, v223
	v_lshlrev_b32_e32 v224, 16, v152
	v_and_b32_e32 v225, 0xffff0000, v152
	v_lshlrev_b32_e32 v226, 16, v153
	v_and_b32_e32 v227, 0xffff0000, v153
	v_lshlrev_b32_e32 v228, 16, v154
	v_and_b32_e32 v229, 0xffff0000, v154
	v_lshlrev_b32_e32 v230, 16, v155
	v_and_b32_e32 v231, 0xffff0000, v155
	v_add_f32_e32 v216, 1.0, v216
	v_add_f32_e32 v217, 1.0, v217
	v_add_f32_e32 v218, 1.0, v218
	v_add_f32_e32 v219, 1.0, v219
	v_add_f32_e32 v220, 1.0, v220
	v_add_f32_e32 v221, 1.0, v221
	v_add_f32_e32 v222, 1.0, v222
	v_add_f32_e32 v223, 1.0, v223
	v_rcp_f32_e32 v216, v216
	v_rcp_f32_e32 v217, v217
	v_rcp_f32_e32 v218, v218
	v_rcp_f32_e32 v219, v219
	v_rcp_f32_e32 v220, v220
	v_rcp_f32_e32 v221, v221
	v_rcp_f32_e32 v222, v222
	v_rcp_f32_e32 v223, v223
	s_nop 0
	v_fma_f32 v216, -v208, v216, v208
	v_fma_f32 v217, -v209, v217, v209
	v_fma_f32 v218, -v210, v218, v210
	v_fma_f32 v219, -v211, v219, v211
	v_fma_f32 v220, -v212, v220, v212
	v_fma_f32 v221, -v213, v221, v213
	v_fma_f32 v222, -v214, v222, v214
	v_fma_f32 v223, -v215, v223, v215
	v_mul_f32_e32 v216, v216, v224
	v_mul_f32_e32 v217, v217, v225
	v_mul_f32_e32 v218, v218, v226
	v_mul_f32_e32 v219, v219, v227
	v_mul_f32_e32 v220, v220, v228
	v_mul_f32_e32 v221, v221, v229
	v_mul_f32_e32 v222, v222, v230
	v_mul_f32_e32 v223, v223, v231
	v_cvt_pk_bf16_f32 v208, v216, v217
	v_cvt_pk_bf16_f32 v209, v218, v219
	v_cvt_pk_bf16_f32 v210, v220, v221
	v_cvt_pk_bf16_f32 v211, v222, v223
	global_store_dwordx4 v197, v[208:211], s[96:97] sc1
	s_movk_i32 s8, 10
.Lact_ctx_loop:
	v_and_b32_e32 v200, 0xff, v172
	v_mad_u32_u24 v197, v172, s15, v199
	v_cmp_ne_u32_e64 s[86:87], 0, v200
	v_cmp_ne_u32_e64 s[88:89], s16, v200
	global_load_dwordx4 v[96:99], v197, s[60:61]
	global_load_dwordx4 v[152:155], v197, s[96:97]
	v_subrev_u32_e32 v201, 0x1600, v197
	v_add_u32_e32 v202, 0x1600, v197
	v_cndmask_b32_e64 v201, v197, v201, s[86:87]
	v_cndmask_b32_e64 v202, v197, v202, s[88:89]
	global_load_dwordx4 v[92:95], v201, s[60:61]
	global_load_dwordx4 v[100:103], v202, s[60:61]
	v_add_u32_e32 v172, s12, v172
	s_waitcnt vmcnt(5)
	v_lshlrev_b32_e32 v216, 16, v132
	v_and_b32_e32 v217, 0xffff0000, v132
	v_lshlrev_b32_e32 v218, 16, v133
	v_and_b32_e32 v219, 0xffff0000, v133
	v_lshlrev_b32_e32 v220, 16, v134
	v_and_b32_e32 v221, 0xffff0000, v134
	v_lshlrev_b32_e32 v222, 16, v135
	v_and_b32_e32 v223, 0xffff0000, v135
	v_fma_f32 v208, v32, v216, v72
	v_fma_f32 v209, v33, v217, v73
	v_fma_f32 v210, v34, v218, v74
	v_fma_f32 v211, v35, v219, v75
	v_fma_f32 v212, v36, v220, v76
	v_fma_f32 v213, v37, v221, v77
	v_fma_f32 v214, v38, v222, v78
	v_fma_f32 v215, v39, v223, v79
	s_mov_b64 exec, s[50:51]
	s_cbranch_execz .Lact_t2_k3
	v_lshlrev_b32_e32 v216, 16, v128
	v_and_b32_e32 v217, 0xffff0000, v128
	v_lshlrev_b32_e32 v218, 16, v129
	v_and_b32_e32 v219, 0xffff0000, v129
	v_lshlrev_b32_e32 v220, 16, v130
	v_and_b32_e32 v221, 0xffff0000, v130
	v_lshlrev_b32_e32 v222, 16, v131
	v_and_b32_e32 v223, 0xffff0000, v131
	v_fmac_f32_e32 v208, v24, v216
	v_fmac_f32_e32 v209, v25, v217
	v_fmac_f32_e32 v210, v26, v218
	v_fmac_f32_e32 v211, v27, v219
	v_fmac_f32_e32 v212, v28, v220
	v_fmac_f32_e32 v213, v29, v221
	v_fmac_f32_e32 v214, v30, v222
	v_fmac_f32_e32 v215, v31, v223
.Lact_t2_k3:
	s_mov_b64 exec, s[52:53]
	s_cbranch_execz .Lact_t2_k5
	v_lshlrev_b32_e32 v216, 16, v136
	v_and_b32_e32 v217, 0xffff0000, v136
	v_lshlrev_b32_e32 v218, 16, v137
	v_and_b32_e32 v219, 0xffff0000, v137
	v_lshlrev_b32_e32 v220, 16, v138
	v_and_b32_e32 v221, 0xffff0000, v138
	v_lshlrev_b32_e32 v222, 16, v139
	v_and_b32_e32 v223, 0xffff0000, v139
	v_fmac_f32_e32 v208, v40, v216
	v_fmac_f32_e32 v209, v41, v217
	v_fmac_f32_e32 v210, v42, v218
	v_fmac_f32_e32 v211, v43, v219
	v_fmac_f32_e32 v212, v44, v220
	v_fmac_f32_e32 v213, v45, v221
	v_fmac_f32_e32 v214, v46, v222
	v_fmac_f32_e32 v215, v47, v223
.Lact_t2_k5:
	s_mov_b64 exec, s[38:39]
	v_mul_f32_e32 v216, v208, v208
	v_mul_f32_e32 v217, v209, v209
	v_mul_f32_e32 v218, v210, v210
	v_mul_f32_e32 v219, v211, v211
	v_mul_f32_e32 v220, v212, v212
	v_mul_f32_e32 v221, v213, v213
	v_mul_f32_e32 v222, v214, v214
	v_mul_f32_e32 v223, v215, v215
	v_mov_b32_e32 v200, 0x40135761
	v_fmamk_f32 v216, v216, 0x3dd2d3e8, v200
	v_fmamk_f32 v217, v217, 0x3dd2d3e8, v200
	v_fmamk_f32 v218, v218, 0x3dd2d3e8, v200
	v_fmamk_f32 v219, v219, 0x3dd2d3e8, v200
	v_fmamk_f32 v220, v220, 0x3dd2d3e8, v200
	v_fmamk_f32 v221, v221, 0x3dd2d3e8, v200
	v_fmamk_f32 v222, v222, 0x3dd2d3e8, v200
	v_fmamk_f32 v223, v223, 0x3dd2d3e8, v200
	v_mul_f32_e32 v216, v216, v208
	v_mul_f32_e32 v217, v217, v209
	v_mul_f32_e32 v218, v218, v210
	v_mul_f32_e32 v219, v219, v211
	v_mul_f32_e32 v220, v220, v212
	v_mul_f32_e32 v221, v221, v213
	v_mul_f32_e32 v222, v222, v214
	v_mul_f32_e32 v223, v223, v215
	v_exp_f32_e32 v216, v216
	v_exp_f32_e32 v217, v217
	v_exp_f32_e32 v218, v218
	v_exp_f32_e32 v219, v219
	v_exp_f32_e32 v220, v220
	v_exp_f32_e32 v221, v221
	v_exp_f32_e32 v222, v222
	v_exp_f32_e32 v223, v223
	v_lshlrev_b32_e32 v224, 16, v156
	v_and_b32_e32 v225, 0xffff0000, v156
	v_lshlrev_b32_e32 v226, 16, v157
	v_and_b32_e32 v227, 0xffff0000, v157
	v_lshlrev_b32_e32 v228, 16, v158
	v_and_b32_e32 v229, 0xffff0000, v158
	v_lshlrev_b32_e32 v230, 16, v159
	v_and_b32_e32 v231, 0xffff0000, v159
	v_add_f32_e32 v216, 1.0, v216
	v_add_f32_e32 v217, 1.0, v217
	v_add_f32_e32 v218, 1.0, v218
	v_add_f32_e32 v219, 1.0, v219
	v_add_f32_e32 v220, 1.0, v220
	v_add_f32_e32 v221, 1.0, v221
	v_add_f32_e32 v222, 1.0, v222
	v_add_f32_e32 v223, 1.0, v223
	v_rcp_f32_e32 v216, v216
	v_rcp_f32_e32 v217, v217
	v_rcp_f32_e32 v218, v218
	v_rcp_f32_e32 v219, v219
	v_rcp_f32_e32 v220, v220
	v_rcp_f32_e32 v221, v221
	v_rcp_f32_e32 v222, v222
	v_rcp_f32_e32 v223, v223
	s_nop 0
	v_fma_f32 v216, -v208, v216, v208
	v_fma_f32 v217, -v209, v217, v209
	v_fma_f32 v218, -v210, v218, v210
	v_fma_f32 v219, -v211, v219, v211
	v_fma_f32 v220, -v212, v220, v212
	v_fma_f32 v221, -v213, v221, v213
	v_fma_f32 v222, -v214, v222, v214
	v_fma_f32 v223, -v215, v223, v215
	v_mul_f32_e32 v216, v216, v224
	v_mul_f32_e32 v217, v217, v225
	v_mul_f32_e32 v218, v218, v226
	v_mul_f32_e32 v219, v219, v227
	v_mul_f32_e32 v220, v220, v228
	v_mul_f32_e32 v221, v221, v229
	v_mul_f32_e32 v222, v222, v230
	v_mul_f32_e32 v223, v223, v231
	v_cvt_pk_bf16_f32 v208, v216, v217
	v_cvt_pk_bf16_f32 v209, v218, v219
	v_cvt_pk_bf16_f32 v210, v220, v221
	v_cvt_pk_bf16_f32 v211, v222, v223
	global_store_dwordx4 v198, v[208:211], s[96:97] sc1
	v_and_b32_e32 v200, 0xff, v172
	v_mad_u32_u24 v198, v172, s15, v199
	v_cmp_ne_u32_e64 s[50:51], 0, v200
	v_cmp_ne_u32_e64 s[52:53], s16, v200
	global_load_dwordx4 v[132:135], v198, s[60:61]
	global_load_dwordx4 v[156:159], v198, s[96:97]
	v_subrev_u32_e32 v201, 0x1600, v198
	v_add_u32_e32 v202, 0x1600, v198
	v_cndmask_b32_e64 v201, v198, v201, s[50:51]
	v_cndmask_b32_e64 v202, v198, v202, s[52:53]
	global_load_dwordx4 v[128:131], v201, s[60:61]
	global_load_dwordx4 v[136:139], v202, s[60:61]
	v_add_u32_e32 v172, s12, v172
	s_waitcnt vmcnt(5)
	v_lshlrev_b32_e32 v216, 16, v96
	v_and_b32_e32 v217, 0xffff0000, v96
	v_lshlrev_b32_e32 v218, 16, v97
	v_and_b32_e32 v219, 0xffff0000, v97
	v_lshlrev_b32_e32 v220, 16, v98
	v_and_b32_e32 v221, 0xffff0000, v98
	v_lshlrev_b32_e32 v222, 16, v99
	v_and_b32_e32 v223, 0xffff0000, v99
	v_fma_f32 v208, v32, v216, v72
	v_fma_f32 v209, v33, v217, v73
	v_fma_f32 v210, v34, v218, v74
	v_fma_f32 v211, v35, v219, v75
	v_fma_f32 v212, v36, v220, v76
	v_fma_f32 v213, v37, v221, v77
	v_fma_f32 v214, v38, v222, v78
	v_fma_f32 v215, v39, v223, v79
	s_mov_b64 exec, s[86:87]
	s_cbranch_execz .Lact_t3_k3
	v_lshlrev_b32_e32 v216, 16, v92
	v_and_b32_e32 v217, 0xffff0000, v92
	v_lshlrev_b32_e32 v218, 16, v93
	v_and_b32_e32 v219, 0xffff0000, v93
	v_lshlrev_b32_e32 v220, 16, v94
	v_and_b32_e32 v221, 0xffff0000, v94
	v_lshlrev_b32_e32 v222, 16, v95
	v_and_b32_e32 v223, 0xffff0000, v95
	v_fmac_f32_e32 v208, v24, v216
	v_fmac_f32_e32 v209, v25, v217
	v_fmac_f32_e32 v210, v26, v218
	v_fmac_f32_e32 v211, v27, v219
	v_fmac_f32_e32 v212, v28, v220
	v_fmac_f32_e32 v213, v29, v221
	v_fmac_f32_e32 v214, v30, v222
	v_fmac_f32_e32 v215, v31, v223

.Lact_t3_k5:
	s_mov_b64 exec, s[38:39]
	v_mul_f32_e32 v216, v208, v208
	v_mul_f32_e32 v217, v209, v209
	v_mul_f32_e32 v218, v210, v210
	v_mul_f32_e32 v219, v211, v211
	v_mul_f32_e32 v220, v212, v212
	v_mul_f32_e32 v221, v213, v213
	v_mul_f32_e32 v222, v214, v214
	v_mul_f32_e32 v223, v215, v215
	v_mov_b32_e32 v200, 0x40135761
	v_fmamk_f32 v216, v216, 0x3dd2d3e8, v200
	v_fmamk_f32 v217, v217, 0x3dd2d3e8, v200
	v_fmamk_f32 v218, v218, 0x3dd2d3e8, v200
	v_fmamk_f32 v219, v219, 0x3dd2d3e8, v200
	v_fmamk_f32 v220, v220, 0x3dd2d3e8, v200
	v_fmamk_f32 v221, v221, 0x3dd2d3e8, v200
	v_fmamk_f32 v222, v222, 0x3dd2d3e8, v200
	v_fmamk_f32 v223, v223, 0x3dd2d3e8, v200
	v_mul_f32_e32 v216, v216, v208
	v_mul_f32_e32 v217, v217, v209
	v_mul_f32_e32 v218, v218, v210
	v_mul_f32_e32 v219, v219, v211
	v_mul_f32_e32 v220, v220, v212
	v_mul_f32_e32 v221, v221, v213
	v_mul_f32_e32 v222, v222, v214
	v_mul_f32_e32 v223, v223, v215
	v_exp_f32_e32 v216, v216
	v_exp_f32_e32 v217, v217
	v_exp_f32_e32 v218, v218
	v_exp_f32_e32 v219, v219
	v_exp_f32_e32 v220, v220
	v_exp_f32_e32 v221, v221
	v_exp_f32_e32 v222, v222
	v_exp_f32_e32 v223, v223
	v_lshlrev_b32_e32 v224, 16, v152
	v_and_b32_e32 v225, 0xffff0000, v152
	v_lshlrev_b32_e32 v226, 16, v153
	v_and_b32_e32 v227, 0xffff0000, v153
	v_lshlrev_b32_e32 v228, 16, v154
	v_and_b32_e32 v229, 0xffff0000, v154
	v_lshlrev_b32_e32 v230, 16, v155
	v_and_b32_e32 v231, 0xffff0000, v155
	v_add_f32_e32 v216, 1.0, v216
	v_add_f32_e32 v217, 1.0, v217
	v_add_f32_e32 v218, 1.0, v218
	v_add_f32_e32 v219, 1.0, v219
	v_add_f32_e32 v220, 1.0, v220
	v_add_f32_e32 v221, 1.0, v221
	v_add_f32_e32 v222, 1.0, v222
	v_add_f32_e32 v223, 1.0, v223
	v_rcp_f32_e32 v216, v216
	v_rcp_f32_e32 v217, v217
	v_rcp_f32_e32 v218, v218
	v_rcp_f32_e32 v219, v219
	v_rcp_f32_e32 v220, v220
	v_rcp_f32_e32 v221, v221
	v_rcp_f32_e32 v222, v222
	v_rcp_f32_e32 v223, v223
	s_nop 0
	v_fma_f32 v216, -v208, v216, v208
	v_fma_f32 v217, -v209, v217, v209
	v_fma_f32 v218, -v210, v218, v210
	v_fma_f32 v219, -v211, v219, v211
	v_fma_f32 v220, -v212, v220, v212
	v_fma_f32 v221, -v213, v221, v213
	v_fma_f32 v222, -v214, v222, v214
	v_fma_f32 v223, -v215, v223, v215
	v_mul_f32_e32 v216, v216, v224
	v_mul_f32_e32 v217, v217, v225
	v_mul_f32_e32 v218, v218, v226
	v_mul_f32_e32 v219, v219, v227
	v_mul_f32_e32 v220, v220, v228
	v_mul_f32_e32 v221, v221, v229
	v_mul_f32_e32 v222, v222, v230
	v_mul_f32_e32 v223, v223, v231
	v_cvt_pk_bf16_f32 v208, v216, v217
	v_cvt_pk_bf16_f32 v209, v218, v219
	v_cvt_pk_bf16_f32 v210, v220, v221
	v_cvt_pk_bf16_f32 v211, v222, v223
	global_store_dwordx4 v197, v[208:211], s[96:97] sc1
	s_sub_u32 s8, s8, 1
	s_cmp_lg_u32 s8, 0
	s_cbranch_scc1 .Lact_ctx_loop
	s_waitcnt vmcnt(1)
	v_lshlrev_b32_e32 v216, 16, v132
	v_and_b32_e32 v217, 0xffff0000, v132
	v_lshlrev_b32_e32 v218, 16, v133
	v_and_b32_e32 v219, 0xffff0000, v133
	v_lshlrev_b32_e32 v220, 16, v134
	v_and_b32_e32 v221, 0xffff0000, v134
	v_lshlrev_b32_e32 v222, 16, v135
	v_and_b32_e32 v223, 0xffff0000, v135
	v_fma_f32 v208, v32, v216, v72
	v_fma_f32 v209, v33, v217, v73
	v_fma_f32 v210, v34, v218, v74
	v_fma_f32 v211, v35, v219, v75
	v_fma_f32 v212, v36, v220, v76
	v_fma_f32 v213, v37, v221, v77
	v_fma_f32 v214, v38, v222, v78
	v_fma_f32 v215, v39, v223, v79
	s_mov_b64 exec, s[50:51]
	s_cbranch_execz .Lact_t4_k3
	v_lshlrev_b32_e32 v216, 16, v128
	v_and_b32_e32 v217, 0xffff0000, v128
	v_lshlrev_b32_e32 v218, 16, v129
	v_and_b32_e32 v219, 0xffff0000, v129
	v_lshlrev_b32_e32 v220, 16, v130
	v_and_b32_e32 v221, 0xffff0000, v130
	v_lshlrev_b32_e32 v222, 16, v131
	v_and_b32_e32 v223, 0xffff0000, v131
	v_fmac_f32_e32 v208, v24, v216
	v_fmac_f32_e32 v209, v25, v217
	v_fmac_f32_e32 v210, v26, v218
	v_fmac_f32_e32 v211, v27, v219
	v_fmac_f32_e32 v212, v28, v220
	v_fmac_f32_e32 v213, v29, v221
	v_fmac_f32_e32 v214, v30, v222
	v_fmac_f32_e32 v215, v31, v223

.Lact_t4_k5:
	s_mov_b64 exec, s[38:39]
	v_mul_f32_e32 v216, v208, v208
	v_mul_f32_e32 v217, v209, v209
	v_mul_f32_e32 v218, v210, v210
	v_mul_f32_e32 v219, v211, v211
	v_mul_f32_e32 v220, v212, v212
	v_mul_f32_e32 v221, v213, v213
	v_mul_f32_e32 v222, v214, v214
	v_mul_f32_e32 v223, v215, v215
	v_mov_b32_e32 v200, 0x40135761
	v_fmamk_f32 v216, v216, 0x3dd2d3e8, v200
	v_fmamk_f32 v217, v217, 0x3dd2d3e8, v200
	v_fmamk_f32 v218, v218, 0x3dd2d3e8, v200
	v_fmamk_f32 v219, v219, 0x3dd2d3e8, v200
	v_fmamk_f32 v220, v220, 0x3dd2d3e8, v200
	v_fmamk_f32 v221, v221, 0x3dd2d3e8, v200
	v_fmamk_f32 v222, v222, 0x3dd2d3e8, v200
	v_fmamk_f32 v223, v223, 0x3dd2d3e8, v200
	v_mul_f32_e32 v216, v216, v208
	v_mul_f32_e32 v217, v217, v209
	v_mul_f32_e32 v218, v218, v210
	v_mul_f32_e32 v219, v219, v211
	v_mul_f32_e32 v220, v220, v212
	v_mul_f32_e32 v221, v221, v213
	v_mul_f32_e32 v222, v222, v214
	v_mul_f32_e32 v223, v223, v215
	v_exp_f32_e32 v216, v216
	v_exp_f32_e32 v217, v217
	v_exp_f32_e32 v218, v218
	v_exp_f32_e32 v219, v219
	v_exp_f32_e32 v220, v220
	v_exp_f32_e32 v221, v221
	v_exp_f32_e32 v222, v222
	v_exp_f32_e32 v223, v223
	v_lshlrev_b32_e32 v224, 16, v156
	v_and_b32_e32 v225, 0xffff0000, v156
	v_lshlrev_b32_e32 v226, 16, v157
	v_and_b32_e32 v227, 0xffff0000, v157
	v_lshlrev_b32_e32 v228, 16, v158
	v_and_b32_e32 v229, 0xffff0000, v158
	v_lshlrev_b32_e32 v230, 16, v159
	v_and_b32_e32 v231, 0xffff0000, v159
	v_add_f32_e32 v216, 1.0, v216
	v_add_f32_e32 v217, 1.0, v217
	v_add_f32_e32 v218, 1.0, v218
	v_add_f32_e32 v219, 1.0, v219
	v_add_f32_e32 v220, 1.0, v220
	v_add_f32_e32 v221, 1.0, v221
	v_add_f32_e32 v222, 1.0, v222
	v_add_f32_e32 v223, 1.0, v223
	v_rcp_f32_e32 v216, v216
	v_rcp_f32_e32 v217, v217
	v_rcp_f32_e32 v218, v218
	v_rcp_f32_e32 v219, v219
	v_rcp_f32_e32 v220, v220
	v_rcp_f32_e32 v221, v221
	v_rcp_f32_e32 v222, v222
	v_rcp_f32_e32 v223, v223
	s_nop 0
	v_fma_f32 v216, -v208, v216, v208
	v_fma_f32 v217, -v209, v217, v209
	v_fma_f32 v218, -v210, v218, v210
	v_fma_f32 v219, -v211, v219, v211
	v_fma_f32 v220, -v212, v220, v212
	v_fma_f32 v221, -v213, v221, v213
	v_fma_f32 v222, -v214, v222, v214
	v_fma_f32 v223, -v215, v223, v215
	v_mul_f32_e32 v216, v216, v224
	v_mul_f32_e32 v217, v217, v225
	v_mul_f32_e32 v218, v218, v226
	v_mul_f32_e32 v219, v219, v227
	v_mul_f32_e32 v220, v220, v228
	v_mul_f32_e32 v221, v221, v229
	v_mul_f32_e32 v222, v222, v230
	v_mul_f32_e32 v223, v223, v231
	v_cvt_pk_bf16_f32 v208, v216, v217
	v_cvt_pk_bf16_f32 v209, v218, v219
	v_cvt_pk_bf16_f32 v210, v220, v221
	v_cvt_pk_bf16_f32 v211, v222, v223
	global_store_dwordx4 v198, v[208:211], s[96:97] sc1
	v_mov_b32_e32 v195, v172
	v_and_b32_e32 v200, 56, v195
	v_lshrrev_b32_e32 v201, 3, v195
	v_and_b32_e32 v201, 56, v201
	v_lshl_or_b32 v200, v200, 3, v201
	v_and_b32_e32 v201, 0xfffffe07, v195
	v_or_b32_e32 v200, v200, v201
	v_cmp_lt_i32_e32 vcc, s14, v195
	s_nop 1
	v_cndmask_b32_e32 v195, v195, v200, vcc
	v_and_b32_e32 v200, 63, v195
	v_bfe_u32 v201, v195, 6, 6
	v_and_b32_e32 v202, 0xff, v195
	v_mov_b32_e32 v216, 0xff
	v_cndmask_b32_e32 v200, v202, v200, vcc
	v_cndmask_b32_e64 v216, v216, 63, vcc
	s_mov_b64 s[0:1], vcc
	v_cmp_ne_u32_e64 s[86:87], 0, v200
	v_cmp_ne_u32_e64 s[88:89], v216, v200
	v_cmp_ne_u32_e64 s[82:83], 0, v201
	v_cmp_ne_u32_e64 s[92:93], 63, v201
	v_mad_u32_u24 v197, v195, s15, v199
	s_and_b64 s[82:83], s[82:83], s[0:1]
	s_and_b64 s[92:93], s[92:93], s[0:1]
	s_and_b64 s[80:81], s[82:83], s[86:87]
	s_and_b64 s[84:85], s[82:83], s[88:89]
	s_and_b64 s[90:91], s[92:93], s[86:87]
	s_and_b64 s[94:95], s[92:93], s[88:89]
	global_load_dwordx4 v[96:99], v197, s[60:61]
	global_load_dwordx4 v[152:155], v197, s[96:97]
	v_subrev_u32_e32 v217, 0x59600, v197
	v_subrev_u32_e32 v218, 0x58000, v197
	v_subrev_u32_e32 v219, 0x56a00, v197
	v_subrev_u32_e32 v220, 0x1600, v197
	v_add_u32_e32 v221, 0x1600, v197
	v_add_u32_e32 v222, 0x56a00, v197
	v_add_u32_e32 v223, 0x58000, v197
	v_add_u32_e32 v224, 0x59600, v197
	s_nop 0
	v_cndmask_b32_e64 v217, v197, v217, s[80:81]
	v_cndmask_b32_e64 v218, v197, v218, s[82:83]
	v_cndmask_b32_e64 v219, v197, v219, s[84:85]
	v_cndmask_b32_e64 v220, v197, v220, s[86:87]
	v_cndmask_b32_e64 v221, v197, v221, s[88:89]
	v_cndmask_b32_e64 v222, v197, v222, s[90:91]
	v_cndmask_b32_e64 v223, v197, v223, s[92:93]
	v_cndmask_b32_e64 v224, v197, v224, s[94:95]
	global_load_dwordx4 v[80:83], v217, s[60:61]
	global_load_dwordx4 v[84:87], v218, s[60:61]
	global_load_dwordx4 v[88:91], v219, s[60:61]
	global_load_dwordx4 v[92:95], v220, s[60:61]
	global_load_dwordx4 v[100:103], v221, s[60:61]
	global_load_dwordx4 v[104:107], v222, s[60:61]
	global_load_dwordx4 v[108:111], v223, s[60:61]
	global_load_dwordx4 v[112:115], v224, s[60:61]
	v_add_u32_e32 v172, s12, v172
	v_mov_b32_e32 v195, v172
	v_and_b32_e32 v200, 56, v195
	v_lshrrev_b32_e32 v201, 3, v195
	v_and_b32_e32 v201, 56, v201
	v_lshl_or_b32 v200, v200, 3, v201
	v_and_b32_e32 v201, 0xfffffe07, v195
	v_or_b32_e32 v200, v200, v201
	v_cmp_lt_i32_e32 vcc, s14, v195
	s_nop 1
	v_cndmask_b32_e32 v195, v195, v200, vcc
	v_and_b32_e32 v200, 63, v195
	v_bfe_u32 v201, v195, 6, 6
	v_and_b32_e32 v202, 0xff, v195
	v_mov_b32_e32 v216, 0xff
	v_cndmask_b32_e32 v200, v202, v200, vcc
	v_cndmask_b32_e64 v216, v216, 63, vcc
	s_mov_b64 s[0:1], vcc
	v_cmp_ne_u32_e64 s[50:51], 0, v200
	v_cmp_ne_u32_e64 s[52:53], v216, v200
	v_cmp_ne_u32_e64 s[46:47], 0, v201
	v_cmp_ne_u32_e64 s[56:57], 63, v201
	v_mad_u32_u24 v198, v195, s15, v199
	s_and_b64 s[46:47], s[46:47], s[0:1]
	s_and_b64 s[56:57], s[56:57], s[0:1]
	s_and_b64 s[44:45], s[46:47], s[50:51]
	s_and_b64 s[48:49], s[46:47], s[52:53]
	s_and_b64 s[54:55], s[56:57], s[50:51]
	s_and_b64 s[58:59], s[56:57], s[52:53]
	global_load_dwordx4 v[132:135], v198, s[60:61]
	global_load_dwordx4 v[156:159], v198, s[96:97]
	v_subrev_u32_e32 v217, 0x59600, v198
	v_subrev_u32_e32 v218, 0x58000, v198
	v_subrev_u32_e32 v219, 0x56a00, v198
	v_subrev_u32_e32 v220, 0x1600, v198
	v_add_u32_e32 v221, 0x1600, v198
	v_add_u32_e32 v222, 0x56a00, v198
	v_add_u32_e32 v223, 0x58000, v198
	v_add_u32_e32 v224, 0x59600, v198
	s_nop 0
	v_cndmask_b32_e64 v217, v198, v217, s[44:45]
	v_cndmask_b32_e64 v218, v198, v218, s[46:47]
	v_cndmask_b32_e64 v219, v198, v219, s[48:49]
	v_cndmask_b32_e64 v220, v198, v220, s[50:51]
	v_cndmask_b32_e64 v221, v198, v221, s[52:53]
	v_cndmask_b32_e64 v222, v198, v222, s[54:55]
	v_cndmask_b32_e64 v223, v198, v223, s[56:57]
	v_cndmask_b32_e64 v224, v198, v224, s[58:59]
	global_load_dwordx4 v[116:119], v217, s[60:61]
	global_load_dwordx4 v[120:123], v218, s[60:61]
	global_load_dwordx4 v[124:127], v219, s[60:61]
	global_load_dwordx4 v[128:131], v220, s[60:61]
	global_load_dwordx4 v[136:139], v221, s[60:61]
	global_load_dwordx4 v[140:143], v222, s[60:61]
	global_load_dwordx4 v[144:147], v223, s[60:61]
	global_load_dwordx4 v[148:151], v224, s[60:61]
	v_add_u32_e32 v172, s12, v172
	s_waitcnt vmcnt(10)
	v_lshlrev_b32_e32 v216, 16, v96
	v_and_b32_e32 v217, 0xffff0000, v96
	v_lshlrev_b32_e32 v218, 16, v97
	v_and_b32_e32 v219, 0xffff0000, v97
	v_lshlrev_b32_e32 v220, 16, v98
	v_and_b32_e32 v221, 0xffff0000, v98
	v_lshlrev_b32_e32 v222, 16, v99
	v_and_b32_e32 v223, 0xffff0000, v99
	v_fma_f32 v208, v32, v216, v72
	v_fma_f32 v209, v33, v217, v73
	v_fma_f32 v210, v34, v218, v74
	v_fma_f32 v211, v35, v219, v75
	v_fma_f32 v212, v36, v220, v76
	v_fma_f32 v213, v37, v221, v77
	v_fma_f32 v214, v38, v222, v78
	v_fma_f32 v215, v39, v223, v79
	s_mov_b64 exec, s[80:81]
	s_cbranch_execz .Lact_t5_k0
	v_lshlrev_b32_e32 v216, 16, v80
	v_and_b32_e32 v217, 0xffff0000, v80
	v_lshlrev_b32_e32 v218, 16, v81
	v_and_b32_e32 v219, 0xffff0000, v81
	v_lshlrev_b32_e32 v220, 16, v82
	v_and_b32_e32 v221, 0xffff0000, v82
	v_lshlrev_b32_e32 v222, 16, v83
	v_and_b32_e32 v223, 0xffff0000, v83
	v_fmac_f32_e32 v208, v0, v216
	v_fmac_f32_e32 v209, v1, v217
	v_fmac_f32_e32 v210, v2, v218
	v_fmac_f32_e32 v211, v3, v219
	v_fmac_f32_e32 v212, v4, v220
	v_fmac_f32_e32 v213, v5, v221
	v_fmac_f32_e32 v214, v6, v222
	v_fmac_f32_e32 v215, v7, v223
.Lact_t5_k0:
	s_mov_b64 exec, s[82:83]
	s_cbranch_execz .Lact_t5_k1
	v_lshlrev_b32_e32 v216, 16, v84
	v_and_b32_e32 v217, 0xffff0000, v84
	v_lshlrev_b32_e32 v218, 16, v85
	v_and_b32_e32 v219, 0xffff0000, v85
	v_lshlrev_b32_e32 v220, 16, v86
	v_and_b32_e32 v221, 0xffff0000, v86
	v_lshlrev_b32_e32 v222, 16, v87
	v_and_b32_e32 v223, 0xffff0000, v87
	v_fmac_f32_e32 v208, v8, v216
	v_fmac_f32_e32 v209, v9, v217
	v_fmac_f32_e32 v210, v10, v218
	v_fmac_f32_e32 v211, v11, v219
	v_fmac_f32_e32 v212, v12, v220
	v_fmac_f32_e32 v213, v13, v221
	v_fmac_f32_e32 v214, v14, v222
	v_fmac_f32_e32 v215, v15, v223
.Lact_t5_k1:
	s_mov_b64 exec, s[84:85]
	s_cbranch_execz .Lact_t5_k2
	v_lshlrev_b32_e32 v216, 16, v88
	v_and_b32_e32 v217, 0xffff0000, v88
	v_lshlrev_b32_e32 v218, 16, v89
	v_and_b32_e32 v219, 0xffff0000, v89
	v_lshlrev_b32_e32 v220, 16, v90
	v_and_b32_e32 v221, 0xffff0000, v90
	v_lshlrev_b32_e32 v222, 16, v91
	v_and_b32_e32 v223, 0xffff0000, v91
	v_fmac_f32_e32 v208, v16, v216
	v_fmac_f32_e32 v209, v17, v217
	v_fmac_f32_e32 v210, v18, v218
	v_fmac_f32_e32 v211, v19, v219
	v_fmac_f32_e32 v212, v20, v220
	v_fmac_f32_e32 v213, v21, v221
	v_fmac_f32_e32 v214, v22, v222
	v_fmac_f32_e32 v215, v23, v223
.Lact_t5_k2:
	s_mov_b64 exec, s[86:87]
	s_cbranch_execz .Lact_t5_k3
	v_lshlrev_b32_e32 v216, 16, v92
	v_and_b32_e32 v217, 0xffff0000, v92
	v_lshlrev_b32_e32 v218, 16, v93
	v_and_b32_e32 v219, 0xffff0000, v93
	v_lshlrev_b32_e32 v220, 16, v94
	v_and_b32_e32 v221, 0xffff0000, v94
	v_lshlrev_b32_e32 v222, 16, v95
	v_and_b32_e32 v223, 0xffff0000, v95
	v_fmac_f32_e32 v208, v24, v216
	v_fmac_f32_e32 v209, v25, v217
	v_fmac_f32_e32 v210, v26, v218
	v_fmac_f32_e32 v211, v27, v219
	v_fmac_f32_e32 v212, v28, v220
	v_fmac_f32_e32 v213, v29, v221
	v_fmac_f32_e32 v214, v30, v222
	v_fmac_f32_e32 v215, v31, v223

.Lact_t5_k5:
	s_mov_b64 exec, s[90:91]
	s_cbranch_execz .Lact_t5_k6
	v_lshlrev_b32_e32 v216, 16, v104
	v_and_b32_e32 v217, 0xffff0000, v104
	v_lshlrev_b32_e32 v218, 16, v105
	v_and_b32_e32 v219, 0xffff0000, v105
	v_lshlrev_b32_e32 v220, 16, v106
	v_and_b32_e32 v221, 0xffff0000, v106
	v_lshlrev_b32_e32 v222, 16, v107
	v_and_b32_e32 v223, 0xffff0000, v107
	v_fmac_f32_e32 v208, v48, v216
	v_fmac_f32_e32 v209, v49, v217
	v_fmac_f32_e32 v210, v50, v218
	v_fmac_f32_e32 v211, v51, v219
	v_fmac_f32_e32 v212, v52, v220
	v_fmac_f32_e32 v213, v53, v221
	v_fmac_f32_e32 v214, v54, v222
	v_fmac_f32_e32 v215, v55, v223
.Lact_t5_k6:
	s_mov_b64 exec, s[92:93]
	s_cbranch_execz .Lact_t5_k7
	v_lshlrev_b32_e32 v216, 16, v108
	v_and_b32_e32 v217, 0xffff0000, v108
	v_lshlrev_b32_e32 v218, 16, v109
	v_and_b32_e32 v219, 0xffff0000, v109
	v_lshlrev_b32_e32 v220, 16, v110
	v_and_b32_e32 v221, 0xffff0000, v110
	v_lshlrev_b32_e32 v222, 16, v111
	v_and_b32_e32 v223, 0xffff0000, v111
	v_fmac_f32_e32 v208, v56, v216
	v_fmac_f32_e32 v209, v57, v217
	v_fmac_f32_e32 v210, v58, v218
	v_fmac_f32_e32 v211, v59, v219
	v_fmac_f32_e32 v212, v60, v220
	v_fmac_f32_e32 v213, v61, v221
	v_fmac_f32_e32 v214, v62, v222
	v_fmac_f32_e32 v215, v63, v223
.Lact_t5_k7:
	s_mov_b64 exec, s[94:95]
	s_cbranch_execz .Lact_t5_k8
	v_lshlrev_b32_e32 v216, 16, v112
	v_and_b32_e32 v217, 0xffff0000, v112
	v_lshlrev_b32_e32 v218, 16, v113
	v_and_b32_e32 v219, 0xffff0000, v113
	v_lshlrev_b32_e32 v220, 16, v114
	v_and_b32_e32 v221, 0xffff0000, v114
	v_lshlrev_b32_e32 v222, 16, v115
	v_and_b32_e32 v223, 0xffff0000, v115
	v_fmac_f32_e32 v208, v64, v216
	v_fmac_f32_e32 v209, v65, v217
	v_fmac_f32_e32 v210, v66, v218
	v_fmac_f32_e32 v211, v67, v219
	v_fmac_f32_e32 v212, v68, v220
	v_fmac_f32_e32 v213, v69, v221
	v_fmac_f32_e32 v214, v70, v222
	v_fmac_f32_e32 v215, v71, v223

.Lact_lat_loop:
	v_mov_b32_e32 v195, v172
	v_and_b32_e32 v200, 56, v195
	v_lshrrev_b32_e32 v201, 3, v195
	v_and_b32_e32 v201, 56, v201
	v_lshl_or_b32 v200, v200, 3, v201
	v_and_b32_e32 v201, 0xfffffe07, v195
	v_or_b32_e32 v200, v200, v201
	v_cmp_lt_i32_e32 vcc, s14, v195
	s_nop 1
	v_cndmask_b32_e32 v195, v195, v200, vcc
	v_and_b32_e32 v200, 63, v195
	v_bfe_u32 v201, v195, 6, 6
	v_and_b32_e32 v202, 0xff, v195
	v_mov_b32_e32 v216, 0xff
	v_cndmask_b32_e32 v200, v202, v200, vcc
	v_cndmask_b32_e64 v216, v216, 63, vcc
	s_mov_b64 s[0:1], vcc
	v_cmp_ne_u32_e64 s[86:87], 0, v200
	v_cmp_ne_u32_e64 s[88:89], v216, v200
	v_cmp_ne_u32_e64 s[82:83], 0, v201
	v_cmp_ne_u32_e64 s[92:93], 63, v201
	v_mad_u32_u24 v197, v195, s15, v199
	s_and_b64 s[82:83], s[82:83], s[0:1]
	s_and_b64 s[92:93], s[92:93], s[0:1]
	s_and_b64 s[80:81], s[82:83], s[86:87]
	s_and_b64 s[84:85], s[82:83], s[88:89]
	s_and_b64 s[90:91], s[92:93], s[86:87]
	s_and_b64 s[94:95], s[92:93], s[88:89]
	global_load_dwordx4 v[96:99], v197, s[60:61]
	global_load_dwordx4 v[152:155], v197, s[96:97]
	v_subrev_u32_e32 v217, 0x59600, v197
	v_subrev_u32_e32 v218, 0x58000, v197
	v_subrev_u32_e32 v219, 0x56a00, v197
	v_subrev_u32_e32 v220, 0x1600, v197
	v_add_u32_e32 v221, 0x1600, v197
	v_add_u32_e32 v222, 0x56a00, v197
	v_add_u32_e32 v223, 0x58000, v197
	v_add_u32_e32 v224, 0x59600, v197
	s_nop 0
	v_cndmask_b32_e64 v217, v197, v217, s[80:81]
	v_cndmask_b32_e64 v218, v197, v218, s[82:83]
	v_cndmask_b32_e64 v219, v197, v219, s[84:85]
	v_cndmask_b32_e64 v220, v197, v220, s[86:87]
	v_cndmask_b32_e64 v221, v197, v221, s[88:89]
	v_cndmask_b32_e64 v222, v197, v222, s[90:91]
	v_cndmask_b32_e64 v223, v197, v223, s[92:93]
	v_cndmask_b32_e64 v224, v197, v224, s[94:95]
	global_load_dwordx4 v[80:83], v217, s[60:61]
	global_load_dwordx4 v[84:87], v218, s[60:61]
	global_load_dwordx4 v[88:91], v219, s[60:61]
	global_load_dwordx4 v[92:95], v220, s[60:61]
	global_load_dwordx4 v[100:103], v221, s[60:61]
	global_load_dwordx4 v[104:107], v222, s[60:61]
	global_load_dwordx4 v[108:111], v223, s[60:61]
	global_load_dwordx4 v[112:115], v224, s[60:61]
	v_add_u32_e32 v172, s12, v172
	s_waitcnt vmcnt(11)
	v_lshlrev_b32_e32 v216, 16, v132
	v_and_b32_e32 v217, 0xffff0000, v132
	v_lshlrev_b32_e32 v218, 16, v133
	v_and_b32_e32 v219, 0xffff0000, v133
	v_lshlrev_b32_e32 v220, 16, v134
	v_and_b32_e32 v221, 0xffff0000, v134
	v_lshlrev_b32_e32 v222, 16, v135
	v_and_b32_e32 v223, 0xffff0000, v135
	v_fma_f32 v208, v32, v216, v72
	v_fma_f32 v209, v33, v217, v73
	v_fma_f32 v210, v34, v218, v74
	v_fma_f32 v211, v35, v219, v75
	v_fma_f32 v212, v36, v220, v76
	v_fma_f32 v213, v37, v221, v77
	v_fma_f32 v214, v38, v222, v78
	v_fma_f32 v215, v39, v223, v79
	s_mov_b64 exec, s[44:45]
	s_cbranch_execz .Lact_t6_k0
	v_lshlrev_b32_e32 v216, 16, v116
	v_and_b32_e32 v217, 0xffff0000, v116
	v_lshlrev_b32_e32 v218, 16, v117
	v_and_b32_e32 v219, 0xffff0000, v117
	v_lshlrev_b32_e32 v220, 16, v118
	v_and_b32_e32 v221, 0xffff0000, v118
	v_lshlrev_b32_e32 v222, 16, v119
	v_and_b32_e32 v223, 0xffff0000, v119
	v_fmac_f32_e32 v208, v0, v216
	v_fmac_f32_e32 v209, v1, v217
	v_fmac_f32_e32 v210, v2, v218
	v_fmac_f32_e32 v211, v3, v219
	v_fmac_f32_e32 v212, v4, v220
	v_fmac_f32_e32 v213, v5, v221
	v_fmac_f32_e32 v214, v6, v222
	v_fmac_f32_e32 v215, v7, v223
.Lact_t6_k0:
	s_mov_b64 exec, s[46:47]
	s_cbranch_execz .Lact_t6_k1
	v_lshlrev_b32_e32 v216, 16, v120
	v_and_b32_e32 v217, 0xffff0000, v120
	v_lshlrev_b32_e32 v218, 16, v121
	v_and_b32_e32 v219, 0xffff0000, v121
	v_lshlrev_b32_e32 v220, 16, v122
	v_and_b32_e32 v221, 0xffff0000, v122
	v_lshlrev_b32_e32 v222, 16, v123
	v_and_b32_e32 v223, 0xffff0000, v123
	v_fmac_f32_e32 v208, v8, v216
	v_fmac_f32_e32 v209, v9, v217
	v_fmac_f32_e32 v210, v10, v218
	v_fmac_f32_e32 v211, v11, v219
	v_fmac_f32_e32 v212, v12, v220
	v_fmac_f32_e32 v213, v13, v221
	v_fmac_f32_e32 v214, v14, v222
	v_fmac_f32_e32 v215, v15, v223
.Lact_t6_k1:
	s_mov_b64 exec, s[48:49]
	s_cbranch_execz .Lact_t6_k2
	v_lshlrev_b32_e32 v216, 16, v124
	v_and_b32_e32 v217, 0xffff0000, v124
	v_lshlrev_b32_e32 v218, 16, v125
	v_and_b32_e32 v219, 0xffff0000, v125
	v_lshlrev_b32_e32 v220, 16, v126
	v_and_b32_e32 v221, 0xffff0000, v126
	v_lshlrev_b32_e32 v222, 16, v127
	v_and_b32_e32 v223, 0xffff0000, v127
	v_fmac_f32_e32 v208, v16, v216
	v_fmac_f32_e32 v209, v17, v217
	v_fmac_f32_e32 v210, v18, v218
	v_fmac_f32_e32 v211, v19, v219
	v_fmac_f32_e32 v212, v20, v220
	v_fmac_f32_e32 v213, v21, v221
	v_fmac_f32_e32 v214, v22, v222
	v_fmac_f32_e32 v215, v23, v223
.Lact_t6_k2:
	s_mov_b64 exec, s[50:51]
	s_cbranch_execz .Lact_t6_k3
	v_lshlrev_b32_e32 v216, 16, v128
	v_and_b32_e32 v217, 0xffff0000, v128
	v_lshlrev_b32_e32 v218, 16, v129
	v_and_b32_e32 v219, 0xffff0000, v129
	v_lshlrev_b32_e32 v220, 16, v130
	v_and_b32_e32 v221, 0xffff0000, v130
	v_lshlrev_b32_e32 v222, 16, v131
	v_and_b32_e32 v223, 0xffff0000, v131
	v_fmac_f32_e32 v208, v24, v216
	v_fmac_f32_e32 v209, v25, v217
	v_fmac_f32_e32 v210, v26, v218
	v_fmac_f32_e32 v211, v27, v219
	v_fmac_f32_e32 v212, v28, v220
	v_fmac_f32_e32 v213, v29, v221
	v_fmac_f32_e32 v214, v30, v222
	v_fmac_f32_e32 v215, v31, v223

.Lact_t6_k5:
	s_mov_b64 exec, s[54:55]
	s_cbranch_execz .Lact_t6_k6
	v_lshlrev_b32_e32 v216, 16, v140
	v_and_b32_e32 v217, 0xffff0000, v140
	v_lshlrev_b32_e32 v218, 16, v141
	v_and_b32_e32 v219, 0xffff0000, v141
	v_lshlrev_b32_e32 v220, 16, v142
	v_and_b32_e32 v221, 0xffff0000, v142
	v_lshlrev_b32_e32 v222, 16, v143
	v_and_b32_e32 v223, 0xffff0000, v143
	v_fmac_f32_e32 v208, v48, v216
	v_fmac_f32_e32 v209, v49, v217
	v_fmac_f32_e32 v210, v50, v218
	v_fmac_f32_e32 v211, v51, v219
	v_fmac_f32_e32 v212, v52, v220
	v_fmac_f32_e32 v213, v53, v221
	v_fmac_f32_e32 v214, v54, v222
	v_fmac_f32_e32 v215, v55, v223
.Lact_t6_k6:
	s_mov_b64 exec, s[56:57]
	s_cbranch_execz .Lact_t6_k7
	v_lshlrev_b32_e32 v216, 16, v144
	v_and_b32_e32 v217, 0xffff0000, v144
	v_lshlrev_b32_e32 v218, 16, v145
	v_and_b32_e32 v219, 0xffff0000, v145
	v_lshlrev_b32_e32 v220, 16, v146
	v_and_b32_e32 v221, 0xffff0000, v146
	v_lshlrev_b32_e32 v222, 16, v147
	v_and_b32_e32 v223, 0xffff0000, v147
	v_fmac_f32_e32 v208, v56, v216
	v_fmac_f32_e32 v209, v57, v217
	v_fmac_f32_e32 v210, v58, v218
	v_fmac_f32_e32 v211, v59, v219
	v_fmac_f32_e32 v212, v60, v220
	v_fmac_f32_e32 v213, v61, v221
	v_fmac_f32_e32 v214, v62, v222
	v_fmac_f32_e32 v215, v63, v223
.Lact_t6_k7:
	s_mov_b64 exec, s[58:59]
	s_cbranch_execz .Lact_t6_k8
	v_lshlrev_b32_e32 v216, 16, v148
	v_and_b32_e32 v217, 0xffff0000, v148
	v_lshlrev_b32_e32 v218, 16, v149
	v_and_b32_e32 v219, 0xffff0000, v149
	v_lshlrev_b32_e32 v220, 16, v150
	v_and_b32_e32 v221, 0xffff0000, v150
	v_lshlrev_b32_e32 v222, 16, v151
	v_and_b32_e32 v223, 0xffff0000, v151
	v_fmac_f32_e32 v208, v64, v216
	v_fmac_f32_e32 v209, v65, v217
	v_fmac_f32_e32 v210, v66, v218
	v_fmac_f32_e32 v211, v67, v219
	v_fmac_f32_e32 v212, v68, v220
	v_fmac_f32_e32 v213, v69, v221
	v_fmac_f32_e32 v214, v70, v222
	v_fmac_f32_e32 v215, v71, v223
.Lact_t6_k8:
	s_mov_b64 exec, s[38:39]
	v_mul_f32_e32 v216, v208, v208
	v_mul_f32_e32 v217, v209, v209
	v_mul_f32_e32 v218, v210, v210
	v_mul_f32_e32 v219, v211, v211
	v_mul_f32_e32 v220, v212, v212
	v_mul_f32_e32 v221, v213, v213
	v_mul_f32_e32 v222, v214, v214
	v_mul_f32_e32 v223, v215, v215
	v_mov_b32_e32 v200, 0x40135761
	v_fmamk_f32 v216, v216, 0x3dd2d3e8, v200
	v_fmamk_f32 v217, v217, 0x3dd2d3e8, v200
	v_fmamk_f32 v218, v218, 0x3dd2d3e8, v200
	v_fmamk_f32 v219, v219, 0x3dd2d3e8, v200
	v_fmamk_f32 v220, v220, 0x3dd2d3e8, v200
	v_fmamk_f32 v221, v221, 0x3dd2d3e8, v200
	v_fmamk_f32 v222, v222, 0x3dd2d3e8, v200
	v_fmamk_f32 v223, v223, 0x3dd2d3e8, v200
	v_mul_f32_e32 v216, v216, v208
	v_mul_f32_e32 v217, v217, v209
	v_mul_f32_e32 v218, v218, v210
	v_mul_f32_e32 v219, v219, v211
	v_mul_f32_e32 v220, v220, v212
	v_mul_f32_e32 v221, v221, v213
	v_mul_f32_e32 v222, v222, v214
	v_mul_f32_e32 v223, v223, v215
	v_exp_f32_e32 v216, v216
	v_exp_f32_e32 v217, v217
	v_exp_f32_e32 v218, v218
	v_exp_f32_e32 v219, v219
	v_exp_f32_e32 v220, v220
	v_exp_f32_e32 v221, v221
	v_exp_f32_e32 v222, v222
	v_exp_f32_e32 v223, v223
	v_lshlrev_b32_e32 v224, 16, v156
	v_and_b32_e32 v225, 0xffff0000, v156
	v_lshlrev_b32_e32 v226, 16, v157
	v_and_b32_e32 v227, 0xffff0000, v157
	v_lshlrev_b32_e32 v228, 16, v158
	v_and_b32_e32 v229, 0xffff0000, v158
	v_lshlrev_b32_e32 v230, 16, v159
	v_and_b32_e32 v231, 0xffff0000, v159
	v_add_f32_e32 v216, 1.0, v216
	v_add_f32_e32 v217, 1.0, v217
	v_add_f32_e32 v218, 1.0, v218
	v_add_f32_e32 v219, 1.0, v219
	v_add_f32_e32 v220, 1.0, v220
	v_add_f32_e32 v221, 1.0, v221
	v_add_f32_e32 v222, 1.0, v222
	v_add_f32_e32 v223, 1.0, v223
	v_rcp_f32_e32 v216, v216
	v_rcp_f32_e32 v217, v217
	v_rcp_f32_e32 v218, v218
	v_rcp_f32_e32 v219, v219
	v_rcp_f32_e32 v220, v220
	v_rcp_f32_e32 v221, v221
	v_rcp_f32_e32 v222, v222
	v_rcp_f32_e32 v223, v223
	s_nop 0
	v_fma_f32 v216, -v208, v216, v208
	v_fma_f32 v217, -v209, v217, v209
	v_fma_f32 v218, -v210, v218, v210
	v_fma_f32 v219, -v211, v219, v211
	v_fma_f32 v220, -v212, v220, v212
	v_fma_f32 v221, -v213, v221, v213
	v_fma_f32 v222, -v214, v222, v214
	v_fma_f32 v223, -v215, v223, v215
	v_mul_f32_e32 v216, v216, v224
	v_mul_f32_e32 v217, v217, v225
	v_mul_f32_e32 v218, v218, v226
	v_mul_f32_e32 v219, v219, v227
	v_mul_f32_e32 v220, v220, v228
	v_mul_f32_e32 v221, v221, v229
	v_mul_f32_e32 v222, v222, v230
	v_mul_f32_e32 v223, v223, v231
	v_cvt_pk_bf16_f32 v208, v216, v217
	v_cvt_pk_bf16_f32 v209, v218, v219
	v_cvt_pk_bf16_f32 v210, v220, v221
	v_cvt_pk_bf16_f32 v211, v222, v223
	global_store_dwordx4 v198, v[208:211], s[96:97] sc1
	v_mov_b32_e32 v195, v172
	v_and_b32_e32 v200, 56, v195
	v_lshrrev_b32_e32 v201, 3, v195
	v_and_b32_e32 v201, 56, v201
	v_lshl_or_b32 v200, v200, 3, v201
	v_and_b32_e32 v201, 0xfffffe07, v195
	v_or_b32_e32 v200, v200, v201
	v_cmp_lt_i32_e32 vcc, s14, v195
	s_nop 1
	v_cndmask_b32_e32 v195, v195, v200, vcc
	v_and_b32_e32 v200, 63, v195
	v_bfe_u32 v201, v195, 6, 6
	v_and_b32_e32 v202, 0xff, v195
	v_mov_b32_e32 v216, 0xff
	v_cndmask_b32_e32 v200, v202, v200, vcc
	v_cndmask_b32_e64 v216, v216, 63, vcc
	s_mov_b64 s[0:1], vcc
	v_cmp_ne_u32_e64 s[50:51], 0, v200
	v_cmp_ne_u32_e64 s[52:53], v216, v200
	v_cmp_ne_u32_e64 s[46:47], 0, v201
	v_cmp_ne_u32_e64 s[56:57], 63, v201
	v_mad_u32_u24 v198, v195, s15, v199
	s_and_b64 s[46:47], s[46:47], s[0:1]
	s_and_b64 s[56:57], s[56:57], s[0:1]
	s_and_b64 s[44:45], s[46:47], s[50:51]
	s_and_b64 s[48:49], s[46:47], s[52:53]
	s_and_b64 s[54:55], s[56:57], s[50:51]
	s_and_b64 s[58:59], s[56:57], s[52:53]
	global_load_dwordx4 v[132:135], v198, s[60:61]
	global_load_dwordx4 v[156:159], v198, s[96:97]
	v_subrev_u32_e32 v217, 0x59600, v198
	v_subrev_u32_e32 v218, 0x58000, v198
	v_subrev_u32_e32 v219, 0x56a00, v198
	v_subrev_u32_e32 v220, 0x1600, v198
	v_add_u32_e32 v221, 0x1600, v198
	v_add_u32_e32 v222, 0x56a00, v198
	v_add_u32_e32 v223, 0x58000, v198
	v_add_u32_e32 v224, 0x59600, v198
	s_nop 0
	v_cndmask_b32_e64 v217, v198, v217, s[44:45]
	v_cndmask_b32_e64 v218, v198, v218, s[46:47]
	v_cndmask_b32_e64 v219, v198, v219, s[48:49]
	v_cndmask_b32_e64 v220, v198, v220, s[50:51]
	v_cndmask_b32_e64 v221, v198, v221, s[52:53]
	v_cndmask_b32_e64 v222, v198, v222, s[54:55]
	v_cndmask_b32_e64 v223, v198, v223, s[56:57]
	v_cndmask_b32_e64 v224, v198, v224, s[58:59]
	global_load_dwordx4 v[116:119], v217, s[60:61]
	global_load_dwordx4 v[120:123], v218, s[60:61]
	global_load_dwordx4 v[124:127], v219, s[60:61]
	global_load_dwordx4 v[128:131], v220, s[60:61]
	global_load_dwordx4 v[136:139], v221, s[60:61]
	global_load_dwordx4 v[140:143], v222, s[60:61]
	global_load_dwordx4 v[144:147], v223, s[60:61]
	global_load_dwordx4 v[148:151], v224, s[60:61]
	v_add_u32_e32 v172, s12, v172
	s_waitcnt vmcnt(11)
	v_lshlrev_b32_e32 v216, 16, v96
	v_and_b32_e32 v217, 0xffff0000, v96
	v_lshlrev_b32_e32 v218, 16, v97
	v_and_b32_e32 v219, 0xffff0000, v97
	v_lshlrev_b32_e32 v220, 16, v98
	v_and_b32_e32 v221, 0xffff0000, v98
	v_lshlrev_b32_e32 v222, 16, v99
	v_and_b32_e32 v223, 0xffff0000, v99
	v_fma_f32 v208, v32, v216, v72
	v_fma_f32 v209, v33, v217, v73
	v_fma_f32 v210, v34, v218, v74
	v_fma_f32 v211, v35, v219, v75
	v_fma_f32 v212, v36, v220, v76
	v_fma_f32 v213, v37, v221, v77
	v_fma_f32 v214, v38, v222, v78
	v_fma_f32 v215, v39, v223, v79
	s_mov_b64 exec, s[80:81]
	s_cbranch_execz .Lact_t7_k0
	v_lshlrev_b32_e32 v216, 16, v80
	v_and_b32_e32 v217, 0xffff0000, v80
	v_lshlrev_b32_e32 v218, 16, v81
	v_and_b32_e32 v219, 0xffff0000, v81
	v_lshlrev_b32_e32 v220, 16, v82
	v_and_b32_e32 v221, 0xffff0000, v82
	v_lshlrev_b32_e32 v222, 16, v83
	v_and_b32_e32 v223, 0xffff0000, v83
	v_fmac_f32_e32 v208, v0, v216
	v_fmac_f32_e32 v209, v1, v217
	v_fmac_f32_e32 v210, v2, v218
	v_fmac_f32_e32 v211, v3, v219
	v_fmac_f32_e32 v212, v4, v220
	v_fmac_f32_e32 v213, v5, v221
	v_fmac_f32_e32 v214, v6, v222
	v_fmac_f32_e32 v215, v7, v223

.Lact_t7_k8:
	s_mov_b64 exec, s[38:39]
	v_mul_f32_e32 v216, v208, v208
	v_mul_f32_e32 v217, v209, v209
	v_mul_f32_e32 v218, v210, v210
	v_mul_f32_e32 v219, v211, v211
	v_mul_f32_e32 v220, v212, v212
	v_mul_f32_e32 v221, v213, v213
	v_mul_f32_e32 v222, v214, v214
	v_mul_f32_e32 v223, v215, v215
	v_mov_b32_e32 v200, 0x40135761
	v_fmamk_f32 v216, v216, 0x3dd2d3e8, v200
	v_fmamk_f32 v217, v217, 0x3dd2d3e8, v200
	v_fmamk_f32 v218, v218, 0x3dd2d3e8, v200
	v_fmamk_f32 v219, v219, 0x3dd2d3e8, v200
	v_fmamk_f32 v220, v220, 0x3dd2d3e8, v200
	v_fmamk_f32 v221, v221, 0x3dd2d3e8, v200
	v_fmamk_f32 v222, v222, 0x3dd2d3e8, v200
	v_fmamk_f32 v223, v223, 0x3dd2d3e8, v200
	v_mul_f32_e32 v216, v216, v208
	v_mul_f32_e32 v217, v217, v209
	v_mul_f32_e32 v218, v218, v210
	v_mul_f32_e32 v219, v219, v211
	v_mul_f32_e32 v220, v220, v212
	v_mul_f32_e32 v221, v221, v213
	v_mul_f32_e32 v222, v222, v214
	v_mul_f32_e32 v223, v223, v215
	v_exp_f32_e32 v216, v216
	v_exp_f32_e32 v217, v217
	v_exp_f32_e32 v218, v218
	v_exp_f32_e32 v219, v219
	v_exp_f32_e32 v220, v220
	v_exp_f32_e32 v221, v221
	v_exp_f32_e32 v222, v222
	v_exp_f32_e32 v223, v223
	v_lshlrev_b32_e32 v224, 16, v152
	v_and_b32_e32 v225, 0xffff0000, v152
	v_lshlrev_b32_e32 v226, 16, v153
	v_and_b32_e32 v227, 0xffff0000, v153
	v_lshlrev_b32_e32 v228, 16, v154
	v_and_b32_e32 v229, 0xffff0000, v154
	v_lshlrev_b32_e32 v230, 16, v155
	v_and_b32_e32 v231, 0xffff0000, v155
	v_add_f32_e32 v216, 1.0, v216
	v_add_f32_e32 v217, 1.0, v217
	v_add_f32_e32 v218, 1.0, v218
	v_add_f32_e32 v219, 1.0, v219
	v_add_f32_e32 v220, 1.0, v220
	v_add_f32_e32 v221, 1.0, v221
	v_add_f32_e32 v222, 1.0, v222
	v_add_f32_e32 v223, 1.0, v223
	v_rcp_f32_e32 v216, v216
	v_rcp_f32_e32 v217, v217
	v_rcp_f32_e32 v218, v218
	v_rcp_f32_e32 v219, v219
	v_rcp_f32_e32 v220, v220
	v_rcp_f32_e32 v221, v221
	v_rcp_f32_e32 v222, v222
	v_rcp_f32_e32 v223, v223
	s_nop 0
	v_fma_f32 v216, -v208, v216, v208
	v_fma_f32 v217, -v209, v217, v209
	v_fma_f32 v218, -v210, v218, v210
	v_fma_f32 v219, -v211, v219, v211
	v_fma_f32 v220, -v212, v220, v212
	v_fma_f32 v221, -v213, v221, v213
	v_fma_f32 v222, -v214, v222, v214
	v_fma_f32 v223, -v215, v223, v215
	v_mul_f32_e32 v216, v216, v224
	v_mul_f32_e32 v217, v217, v225
	v_mul_f32_e32 v218, v218, v226
	v_mul_f32_e32 v219, v219, v227
	v_mul_f32_e32 v220, v220, v228
	v_mul_f32_e32 v221, v221, v229
	v_mul_f32_e32 v222, v222, v230
	v_mul_f32_e32 v223, v223, v231
	v_cvt_pk_bf16_f32 v208, v216, v217
	v_cvt_pk_bf16_f32 v209, v218, v219
	v_cvt_pk_bf16_f32 v210, v220, v221
	v_cvt_pk_bf16_f32 v211, v222, v223
	global_store_dwordx4 v197, v[208:211], s[96:97] sc1
	s_sub_u32 s8, s8, 1
	s_cmp_lg_u32 s8, 0
	s_cbranch_scc1 .Lact_lat_loop
	s_waitcnt vmcnt(1)
	v_lshlrev_b32_e32 v216, 16, v132
	v_and_b32_e32 v217, 0xffff0000, v132
	v_lshlrev_b32_e32 v218, 16, v133
	v_and_b32_e32 v219, 0xffff0000, v133
	v_lshlrev_b32_e32 v220, 16, v134
	v_and_b32_e32 v221, 0xffff0000, v134
	v_lshlrev_b32_e32 v222, 16, v135
	v_and_b32_e32 v223, 0xffff0000, v135
	v_fma_f32 v208, v32, v216, v72
	v_fma_f32 v209, v33, v217, v73
	v_fma_f32 v210, v34, v218, v74
	v_fma_f32 v211, v35, v219, v75
	v_fma_f32 v212, v36, v220, v76
	v_fma_f32 v213, v37, v221, v77
	v_fma_f32 v214, v38, v222, v78
	v_fma_f32 v215, v39, v223, v79
	s_mov_b64 exec, s[44:45]
	s_cbranch_execz .Lact_t8_k0
	v_lshlrev_b32_e32 v216, 16, v116
	v_and_b32_e32 v217, 0xffff0000, v116
	v_lshlrev_b32_e32 v218, 16, v117
	v_and_b32_e32 v219, 0xffff0000, v117
	v_lshlrev_b32_e32 v220, 16, v118
	v_and_b32_e32 v221, 0xffff0000, v118
	v_lshlrev_b32_e32 v222, 16, v119
	v_and_b32_e32 v223, 0xffff0000, v119
	v_fmac_f32_e32 v208, v0, v216
	v_fmac_f32_e32 v209, v1, v217
	v_fmac_f32_e32 v210, v2, v218
	v_fmac_f32_e32 v211, v3, v219
	v_fmac_f32_e32 v212, v4, v220
	v_fmac_f32_e32 v213, v5, v221
	v_fmac_f32_e32 v214, v6, v222
	v_fmac_f32_e32 v215, v7, v223

.Lact_t8_k8:
	s_mov_b64 exec, s[38:39]
	v_mul_f32_e32 v216, v208, v208
	v_mul_f32_e32 v217, v209, v209
	v_mul_f32_e32 v218, v210, v210
	v_mul_f32_e32 v219, v211, v211
	v_mul_f32_e32 v220, v212, v212
	v_mul_f32_e32 v221, v213, v213
	v_mul_f32_e32 v222, v214, v214
	v_mul_f32_e32 v223, v215, v215
	v_mov_b32_e32 v200, 0x40135761
	v_fmamk_f32 v216, v216, 0x3dd2d3e8, v200
	v_fmamk_f32 v217, v217, 0x3dd2d3e8, v200
	v_fmamk_f32 v218, v218, 0x3dd2d3e8, v200
	v_fmamk_f32 v219, v219, 0x3dd2d3e8, v200
	v_fmamk_f32 v220, v220, 0x3dd2d3e8, v200
	v_fmamk_f32 v221, v221, 0x3dd2d3e8, v200
	v_fmamk_f32 v222, v222, 0x3dd2d3e8, v200
	v_fmamk_f32 v223, v223, 0x3dd2d3e8, v200
	v_mul_f32_e32 v216, v216, v208
	v_mul_f32_e32 v217, v217, v209
	v_mul_f32_e32 v218, v218, v210
	v_mul_f32_e32 v219, v219, v211
	v_mul_f32_e32 v220, v220, v212
	v_mul_f32_e32 v221, v221, v213
	v_mul_f32_e32 v222, v222, v214
	v_mul_f32_e32 v223, v223, v215
	v_exp_f32_e32 v216, v216
	v_exp_f32_e32 v217, v217
	v_exp_f32_e32 v218, v218
	v_exp_f32_e32 v219, v219
	v_exp_f32_e32 v220, v220
	v_exp_f32_e32 v221, v221
	v_exp_f32_e32 v222, v222
	v_exp_f32_e32 v223, v223
	v_lshlrev_b32_e32 v224, 16, v156
	v_and_b32_e32 v225, 0xffff0000, v156
	v_lshlrev_b32_e32 v226, 16, v157
	v_and_b32_e32 v227, 0xffff0000, v157
	v_lshlrev_b32_e32 v228, 16, v158
	v_and_b32_e32 v229, 0xffff0000, v158
	v_lshlrev_b32_e32 v230, 16, v159
	v_and_b32_e32 v231, 0xffff0000, v159
	v_add_f32_e32 v216, 1.0, v216
	v_add_f32_e32 v217, 1.0, v217
	v_add_f32_e32 v218, 1.0, v218
	v_add_f32_e32 v219, 1.0, v219
	v_add_f32_e32 v220, 1.0, v220
	v_add_f32_e32 v221, 1.0, v221
	v_add_f32_e32 v222, 1.0, v222
	v_add_f32_e32 v223, 1.0, v223
	v_rcp_f32_e32 v216, v216
	v_rcp_f32_e32 v217, v217
	v_rcp_f32_e32 v218, v218
	v_rcp_f32_e32 v219, v219
	v_rcp_f32_e32 v220, v220
	v_rcp_f32_e32 v221, v221
	v_rcp_f32_e32 v222, v222
	v_rcp_f32_e32 v223, v223
	s_nop 0
	v_fma_f32 v216, -v208, v216, v208
	v_fma_f32 v217, -v209, v217, v209
	v_fma_f32 v218, -v210, v218, v210
	v_fma_f32 v219, -v211, v219, v211
	v_fma_f32 v220, -v212, v220, v212
	v_fma_f32 v221, -v213, v221, v213
	v_fma_f32 v222, -v214, v222, v214
	v_fma_f32 v223, -v215, v223, v215
	v_mul_f32_e32 v216, v216, v224
	v_mul_f32_e32 v217, v217, v225
	v_mul_f32_e32 v218, v218, v226
	v_mul_f32_e32 v219, v219, v227
	v_mul_f32_e32 v220, v220, v228
	v_mul_f32_e32 v221, v221, v229
	v_mul_f32_e32 v222, v222, v230
	v_mul_f32_e32 v223, v223, v231
	v_cvt_pk_bf16_f32 v208, v216, v217
	v_cvt_pk_bf16_f32 v209, v218, v219
	v_cvt_pk_bf16_f32 v210, v220, v221
	v_cvt_pk_bf16_f32 v211, v222, v223
	global_store_dwordx4 v198, v[208:211], s[96:97] sc1
	v_cmp_gt_i32_e32 vcc, s13, v172
	s_and_b64 exec, exec, vcc
	s_cbranch_execz .Lact_done
	s_mov_b64 s[38:39], exec
	v_mov_b32_e32 v195, v172
	v_and_b32_e32 v200, 56, v195
	v_lshrrev_b32_e32 v201, 3, v195
	v_and_b32_e32 v201, 56, v201
	v_lshl_or_b32 v200, v200, 3, v201
	v_and_b32_e32 v201, 0xfffffe07, v195
	v_or_b32_e32 v200, v200, v201
	v_cmp_lt_i32_e32 vcc, s14, v195
	s_nop 1
	v_cndmask_b32_e32 v195, v195, v200, vcc
	v_and_b32_e32 v200, 63, v195
	v_bfe_u32 v201, v195, 6, 6
	v_and_b32_e32 v202, 0xff, v195
	v_mov_b32_e32 v216, 0xff
	v_cndmask_b32_e32 v200, v202, v200, vcc
	v_cndmask_b32_e64 v216, v216, 63, vcc
	s_mov_b64 s[0:1], vcc
	v_cmp_ne_u32_e64 s[86:87], 0, v200
	v_cmp_ne_u32_e64 s[88:89], v216, v200
	v_cmp_ne_u32_e64 s[82:83], 0, v201
	v_cmp_ne_u32_e64 s[92:93], 63, v201
	v_mad_u32_u24 v197, v195, s15, v199
	s_and_b64 s[82:83], s[82:83], s[0:1]
	s_and_b64 s[92:93], s[92:93], s[0:1]
	s_and_b64 s[80:81], s[82:83], s[86:87]
	s_and_b64 s[84:85], s[82:83], s[88:89]
	s_and_b64 s[90:91], s[92:93], s[86:87]
	s_and_b64 s[94:95], s[92:93], s[88:89]
	global_load_dwordx4 v[96:99], v197, s[60:61]
	global_load_dwordx4 v[152:155], v197, s[96:97]
	v_subrev_u32_e32 v217, 0x59600, v197
	v_subrev_u32_e32 v218, 0x58000, v197
	v_subrev_u32_e32 v219, 0x56a00, v197
	v_subrev_u32_e32 v220, 0x1600, v197
	v_add_u32_e32 v221, 0x1600, v197
	v_add_u32_e32 v222, 0x56a00, v197
	v_add_u32_e32 v223, 0x58000, v197
	v_add_u32_e32 v224, 0x59600, v197
	s_nop 0
	v_cndmask_b32_e64 v217, v197, v217, s[80:81]
	v_cndmask_b32_e64 v218, v197, v218, s[82:83]
	v_cndmask_b32_e64 v219, v197, v219, s[84:85]
	v_cndmask_b32_e64 v220, v197, v220, s[86:87]
	v_cndmask_b32_e64 v221, v197, v221, s[88:89]
	v_cndmask_b32_e64 v222, v197, v222, s[90:91]
	v_cndmask_b32_e64 v223, v197, v223, s[92:93]
	v_cndmask_b32_e64 v224, v197, v224, s[94:95]
	global_load_dwordx4 v[80:83], v217, s[60:61]
	global_load_dwordx4 v[84:87], v218, s[60:61]
	global_load_dwordx4 v[88:91], v219, s[60:61]
	global_load_dwordx4 v[92:95], v220, s[60:61]
	global_load_dwordx4 v[100:103], v221, s[60:61]
	global_load_dwordx4 v[104:107], v222, s[60:61]
	global_load_dwordx4 v[108:111], v223, s[60:61]
	global_load_dwordx4 v[112:115], v224, s[60:61]
	s_waitcnt vmcnt(0)
	v_lshlrev_b32_e32 v216, 16, v96
	v_and_b32_e32 v217, 0xffff0000, v96
	v_lshlrev_b32_e32 v218, 16, v97
	v_and_b32_e32 v219, 0xffff0000, v97
	v_lshlrev_b32_e32 v220, 16, v98
	v_and_b32_e32 v221, 0xffff0000, v98
	v_lshlrev_b32_e32 v222, 16, v99
	v_and_b32_e32 v223, 0xffff0000, v99
	v_fma_f32 v208, v32, v216, v72
	v_fma_f32 v209, v33, v217, v73
	v_fma_f32 v210, v34, v218, v74
	v_fma_f32 v211, v35, v219, v75
	v_fma_f32 v212, v36, v220, v76
	v_fma_f32 v213, v37, v221, v77
	v_fma_f32 v214, v38, v222, v78
	v_fma_f32 v215, v39, v223, v79
	s_mov_b64 exec, s[80:81]
	s_cbranch_execz .Lact_t9_k0
	v_lshlrev_b32_e32 v216, 16, v80
	v_and_b32_e32 v217, 0xffff0000, v80
	v_lshlrev_b32_e32 v218, 16, v81
	v_and_b32_e32 v219, 0xffff0000, v81
	v_lshlrev_b32_e32 v220, 16, v82
	v_and_b32_e32 v221, 0xffff0000, v82
	v_lshlrev_b32_e32 v222, 16, v83
	v_and_b32_e32 v223, 0xffff0000, v83
	v_fmac_f32_e32 v208, v0, v216
	v_fmac_f32_e32 v209, v1, v217
	v_fmac_f32_e32 v210, v2, v218
	v_fmac_f32_e32 v211, v3, v219
	v_fmac_f32_e32 v212, v4, v220
	v_fmac_f32_e32 v213, v5, v221
	v_fmac_f32_e32 v214, v6, v222
	v_fmac_f32_e32 v215, v7, v223

.Lact_t9_k8:
	s_mov_b64 exec, s[38:39]
	v_mul_f32_e32 v216, v208, v208
	v_mul_f32_e32 v217, v209, v209
	v_mul_f32_e32 v218, v210, v210
	v_mul_f32_e32 v219, v211, v211
	v_mul_f32_e32 v220, v212, v212
	v_mul_f32_e32 v221, v213, v213
	v_mul_f32_e32 v222, v214, v214
	v_mul_f32_e32 v223, v215, v215
	v_mov_b32_e32 v200, 0x40135761
	v_fmamk_f32 v216, v216, 0x3dd2d3e8, v200
	v_fmamk_f32 v217, v217, 0x3dd2d3e8, v200
	v_fmamk_f32 v218, v218, 0x3dd2d3e8, v200
	v_fmamk_f32 v219, v219, 0x3dd2d3e8, v200
	v_fmamk_f32 v220, v220, 0x3dd2d3e8, v200
	v_fmamk_f32 v221, v221, 0x3dd2d3e8, v200
	v_fmamk_f32 v222, v222, 0x3dd2d3e8, v200
	v_fmamk_f32 v223, v223, 0x3dd2d3e8, v200
	v_mul_f32_e32 v216, v216, v208
	v_mul_f32_e32 v217, v217, v209
	v_mul_f32_e32 v218, v218, v210
	v_mul_f32_e32 v219, v219, v211
	v_mul_f32_e32 v220, v220, v212
	v_mul_f32_e32 v221, v221, v213
	v_mul_f32_e32 v222, v222, v214
	v_mul_f32_e32 v223, v223, v215
	v_exp_f32_e32 v216, v216
	v_exp_f32_e32 v217, v217
	v_exp_f32_e32 v218, v218
	v_exp_f32_e32 v219, v219
	v_exp_f32_e32 v220, v220
	v_exp_f32_e32 v221, v221
	v_exp_f32_e32 v222, v222
	v_exp_f32_e32 v223, v223
	v_lshlrev_b32_e32 v224, 16, v152
	v_and_b32_e32 v225, 0xffff0000, v152
	v_lshlrev_b32_e32 v226, 16, v153
	v_and_b32_e32 v227, 0xffff0000, v153
	v_lshlrev_b32_e32 v228, 16, v154
	v_and_b32_e32 v229, 0xffff0000, v154
	v_lshlrev_b32_e32 v230, 16, v155
	v_and_b32_e32 v231, 0xffff0000, v155
	v_add_f32_e32 v216, 1.0, v216
	v_add_f32_e32 v217, 1.0, v217
	v_add_f32_e32 v218, 1.0, v218
	v_add_f32_e32 v219, 1.0, v219
	v_add_f32_e32 v220, 1.0, v220
	v_add_f32_e32 v221, 1.0, v221
	v_add_f32_e32 v222, 1.0, v222
	v_add_f32_e32 v223, 1.0, v223
	v_rcp_f32_e32 v216, v216
	v_rcp_f32_e32 v217, v217
	v_rcp_f32_e32 v218, v218
	v_rcp_f32_e32 v219, v219
	v_rcp_f32_e32 v220, v220
	v_rcp_f32_e32 v221, v221
	v_rcp_f32_e32 v222, v222
	v_rcp_f32_e32 v223, v223
	s_nop 0
	v_fma_f32 v216, -v208, v216, v208
	v_fma_f32 v217, -v209, v217, v209
	v_fma_f32 v218, -v210, v218, v210
	v_fma_f32 v219, -v211, v219, v211
	v_fma_f32 v220, -v212, v220, v212
	v_fma_f32 v221, -v213, v221, v213
	v_fma_f32 v222, -v214, v222, v214
	v_fma_f32 v223, -v215, v223, v215
	v_mul_f32_e32 v216, v216, v224
	v_mul_f32_e32 v217, v217, v225
	v_mul_f32_e32 v218, v218, v226
	v_mul_f32_e32 v219, v219, v227
	v_mul_f32_e32 v220, v220, v228
	v_mul_f32_e32 v221, v221, v229
	v_mul_f32_e32 v222, v222, v230
	v_mul_f32_e32 v223, v223, v231
	v_cvt_pk_bf16_f32 v208, v216, v217
	v_cvt_pk_bf16_f32 v209, v218, v219
	v_cvt_pk_bf16_f32 v210, v220, v221
	v_cvt_pk_bf16_f32 v211, v222, v223
	global_store_dwordx4 v197, v[208:211], s[96:97] sc1
.Lact_done:
	s_branch .LBB0_1447
